# MoE gate/up L0 epilogue rewritten: DPP lane-pair exchange, 32 dword stores per tile instead of 64 short stores
# baseline (speedup 1.0000x reference)
.LBB0_1183:
	s_waitcnt vmcnt(15)
	v_and_b32_e32 v120, 0xffffff80, v252
	v_lshrrev_b32_e32 v121, 2, v252
	v_and_or_b32 v120, v121, 12, v120
	v_add_u32_e32 v120, s4, v120
	v_and_b32_e32 v121, 1, v252
	v_add_u32_e32 v120, v120, v121
	v_lshlrev_b32_e32 v122, 5, v251
	v_or3_b32 v122, s6, v122, v218
	v_sub_u32_e32 v122, v122, v121
	v_lshlrev_b32_e32 v120, 12, v120
	v_lshl_add_u32 v120, v122, 1, v120
	v_add_u32_e32 v123, 0x2000, v120
	v_cmp_eq_u32_e64 s[98:99], 0, v121
	s_lshl_b64 s[2:3], s[8:9], 1
	v_readlane_b32 s8, v253, 2
	v_readlane_b32 s9, v253, 3
	s_nop 1
	s_add_u32 s2, s8, s2
	s_addc_u32 s3, s9, s3
	v_mul_f32_e32 v124, 0xbfb8aa3b, v156
	v_mul_f32_e32 v125, 0xbfb8aa3b, v157
	v_mul_f32_e32 v126, 0xbfb8aa3b, v158
	v_mul_f32_e32 v127, 0xbfb8aa3b, v159
	v_exp_f32_e32 v124, v124
	v_exp_f32_e32 v125, v125
	v_exp_f32_e32 v126, v126
	v_exp_f32_e32 v127, v127
	v_add_f32_e32 v124, 1.0, v124
	v_add_f32_e32 v125, 1.0, v125
	v_add_f32_e32 v126, 1.0, v126
	v_add_f32_e32 v127, 1.0, v127
	v_rcp_f32_e32 v124, v124
	v_rcp_f32_e32 v125, v125
	v_rcp_f32_e32 v126, v126
	v_rcp_f32_e32 v127, v127
	v_mul_f32_e32 v124, v156, v124
	v_mul_f32_e32 v125, v157, v125
	v_mul_f32_e32 v126, v158, v126
	v_mul_f32_e32 v127, v159, v127
	v_mul_f32_e32 v124, v148, v124
	v_mul_f32_e32 v125, v149, v125
	v_mul_f32_e32 v126, v150, v126
	v_mul_f32_e32 v127, v151, v127
	v_cndmask_b32_e64 v128, v124, v125, s[98:99]
	v_cndmask_b32_e64 v129, v126, v127, s[98:99]
	s_nop 1
	v_mov_b32_dpp v130, v128 quad_perm:[1,0,3,2] row_mask:0xf bank_mask:0xf
	v_mov_b32_dpp v131, v129 quad_perm:[1,0,3,2] row_mask:0xf bank_mask:0xf
	s_nop 0
	v_cndmask_b32_e64 v128, v130, v124, s[98:99]
	v_cndmask_b32_e64 v129, v125, v130, s[98:99]
	v_cndmask_b32_e64 v132, v131, v126, s[98:99]
	v_cndmask_b32_e64 v133, v127, v131, s[98:99]
	v_cvt_pk_bf16_f32 v128, v128, v129
	v_cvt_pk_bf16_f32 v132, v132, v133
	global_store_dword v120, v128, s[2:3]
	global_store_dword v123, v132, s[2:3]
	v_mul_f32_e32 v124, 0xbfb8aa3b, v116
	v_mul_f32_e32 v125, 0xbfb8aa3b, v117
	v_mul_f32_e32 v126, 0xbfb8aa3b, v118
	v_mul_f32_e32 v127, 0xbfb8aa3b, v119
	v_exp_f32_e32 v124, v124
	v_exp_f32_e32 v125, v125
	v_exp_f32_e32 v126, v126
	v_exp_f32_e32 v127, v127
	v_add_f32_e32 v124, 1.0, v124
	v_add_f32_e32 v125, 1.0, v125
	v_add_f32_e32 v126, 1.0, v126
	v_add_f32_e32 v127, 1.0, v127
	v_rcp_f32_e32 v124, v124
	v_rcp_f32_e32 v125, v125
	v_rcp_f32_e32 v126, v126
	v_rcp_f32_e32 v127, v127
	v_mul_f32_e32 v124, v116, v124
	v_mul_f32_e32 v125, v117, v125
	v_mul_f32_e32 v126, v118, v126
	v_mul_f32_e32 v127, v119, v127
	v_mul_f32_e32 v124, v112, v124
	v_mul_f32_e32 v125, v113, v125
	v_mul_f32_e32 v126, v114, v126
	v_mul_f32_e32 v127, v115, v127
	v_cndmask_b32_e64 v128, v124, v125, s[98:99]
	v_cndmask_b32_e64 v129, v126, v127, s[98:99]
	s_nop 1
	v_mov_b32_dpp v130, v128 quad_perm:[1,0,3,2] row_mask:0xf bank_mask:0xf
	v_mov_b32_dpp v131, v129 quad_perm:[1,0,3,2] row_mask:0xf bank_mask:0xf
	s_nop 0
	v_cndmask_b32_e64 v128, v130, v124, s[98:99]
	v_cndmask_b32_e64 v129, v125, v130, s[98:99]
	v_cndmask_b32_e64 v132, v131, v126, s[98:99]
	v_cndmask_b32_e64 v133, v127, v131, s[98:99]
	v_cvt_pk_bf16_f32 v128, v128, v129
	v_cvt_pk_bf16_f32 v132, v132, v133
	global_store_dword v120, v128, s[2:3] offset:32
	global_store_dword v123, v132, s[2:3] offset:32
	s_add_u32 s2, s2, 0x10000
	s_addc_u32 s3, s3, 0
	v_mul_f32_e32 v124, 0xbfb8aa3b, v108
	v_mul_f32_e32 v125, 0xbfb8aa3b, v109
	v_mul_f32_e32 v126, 0xbfb8aa3b, v110
	v_mul_f32_e32 v127, 0xbfb8aa3b, v111
	v_exp_f32_e32 v124, v124
	v_exp_f32_e32 v125, v125
	v_exp_f32_e32 v126, v126
	v_exp_f32_e32 v127, v127
	v_add_f32_e32 v124, 1.0, v124
	v_add_f32_e32 v125, 1.0, v125
	v_add_f32_e32 v126, 1.0, v126
	v_add_f32_e32 v127, 1.0, v127
	v_rcp_f32_e32 v124, v124
	v_rcp_f32_e32 v125, v125
	v_rcp_f32_e32 v126, v126
	v_rcp_f32_e32 v127, v127
	v_mul_f32_e32 v124, v108, v124
	v_mul_f32_e32 v125, v109, v125
	v_mul_f32_e32 v126, v110, v126
	v_mul_f32_e32 v127, v111, v127
	v_mul_f32_e32 v124, v104, v124
	v_mul_f32_e32 v125, v105, v125
	v_mul_f32_e32 v126, v106, v126
	v_mul_f32_e32 v127, v107, v127
	v_cndmask_b32_e64 v128, v124, v125, s[98:99]
	v_cndmask_b32_e64 v129, v126, v127, s[98:99]
	s_nop 1
	v_mov_b32_dpp v130, v128 quad_perm:[1,0,3,2] row_mask:0xf bank_mask:0xf
	v_mov_b32_dpp v131, v129 quad_perm:[1,0,3,2] row_mask:0xf bank_mask:0xf
	s_nop 0
	v_cndmask_b32_e64 v128, v130, v124, s[98:99]
	v_cndmask_b32_e64 v129, v125, v130, s[98:99]
	v_cndmask_b32_e64 v132, v131, v126, s[98:99]
	v_cndmask_b32_e64 v133, v127, v131, s[98:99]
	v_cvt_pk_bf16_f32 v128, v128, v129
	v_cvt_pk_bf16_f32 v132, v132, v133
	global_store_dword v120, v128, s[2:3]
	global_store_dword v123, v132, s[2:3]
	v_mul_f32_e32 v124, 0xbfb8aa3b, v100
	v_mul_f32_e32 v125, 0xbfb8aa3b, v101
	v_mul_f32_e32 v126, 0xbfb8aa3b, v102
	v_mul_f32_e32 v127, 0xbfb8aa3b, v103
	v_exp_f32_e32 v124, v124
	v_exp_f32_e32 v125, v125
	v_exp_f32_e32 v126, v126
	v_exp_f32_e32 v127, v127
	v_add_f32_e32 v124, 1.0, v124
	v_add_f32_e32 v125, 1.0, v125
	v_add_f32_e32 v126, 1.0, v126
	v_add_f32_e32 v127, 1.0, v127
	v_rcp_f32_e32 v124, v124
	v_rcp_f32_e32 v125, v125
	v_rcp_f32_e32 v126, v126
	v_rcp_f32_e32 v127, v127
	v_mul_f32_e32 v124, v100, v124
	v_mul_f32_e32 v125, v101, v125
	v_mul_f32_e32 v126, v102, v126
	v_mul_f32_e32 v127, v103, v127
	v_mul_f32_e32 v124, v96, v124
	v_mul_f32_e32 v125, v97, v125
	v_mul_f32_e32 v126, v98, v126
	v_mul_f32_e32 v127, v99, v127
	v_cndmask_b32_e64 v128, v124, v125, s[98:99]
	v_cndmask_b32_e64 v129, v126, v127, s[98:99]
	s_nop 1
	v_mov_b32_dpp v130, v128 quad_perm:[1,0,3,2] row_mask:0xf bank_mask:0xf
	v_mov_b32_dpp v131, v129 quad_perm:[1,0,3,2] row_mask:0xf bank_mask:0xf
	s_nop 0
	v_cndmask_b32_e64 v128, v130, v124, s[98:99]
	v_cndmask_b32_e64 v129, v125, v130, s[98:99]
	v_cndmask_b32_e64 v132, v131, v126, s[98:99]
	v_cndmask_b32_e64 v133, v127, v131, s[98:99]
	v_cvt_pk_bf16_f32 v128, v128, v129
	v_cvt_pk_bf16_f32 v132, v132, v133
	global_store_dword v120, v128, s[2:3] offset:32
	global_store_dword v123, v132, s[2:3] offset:32
	s_add_u32 s2, s2, 0x10000
	s_addc_u32 s3, s3, 0
	v_mul_f32_e32 v124, 0xbfb8aa3b, v92
	v_mul_f32_e32 v125, 0xbfb8aa3b, v93
	v_mul_f32_e32 v126, 0xbfb8aa3b, v94
	v_mul_f32_e32 v127, 0xbfb8aa3b, v95
	v_exp_f32_e32 v124, v124
	v_exp_f32_e32 v125, v125
	v_exp_f32_e32 v126, v126
	v_exp_f32_e32 v127, v127
	v_add_f32_e32 v124, 1.0, v124
	v_add_f32_e32 v125, 1.0, v125
	v_add_f32_e32 v126, 1.0, v126
	v_add_f32_e32 v127, 1.0, v127
	v_rcp_f32_e32 v124, v124
	v_rcp_f32_e32 v125, v125
	v_rcp_f32_e32 v126, v126
	v_rcp_f32_e32 v127, v127
	v_mul_f32_e32 v124, v92, v124
	v_mul_f32_e32 v125, v93, v125
	v_mul_f32_e32 v126, v94, v126
	v_mul_f32_e32 v127, v95, v127
	v_mul_f32_e32 v124, v88, v124
	v_mul_f32_e32 v125, v89, v125
	v_mul_f32_e32 v126, v90, v126
	v_mul_f32_e32 v127, v91, v127
	v_cndmask_b32_e64 v128, v124, v125, s[98:99]
	v_cndmask_b32_e64 v129, v126, v127, s[98:99]
	s_nop 1
	v_mov_b32_dpp v130, v128 quad_perm:[1,0,3,2] row_mask:0xf bank_mask:0xf
	v_mov_b32_dpp v131, v129 quad_perm:[1,0,3,2] row_mask:0xf bank_mask:0xf
	s_nop 0
	v_cndmask_b32_e64 v128, v130, v124, s[98:99]
	v_cndmask_b32_e64 v129, v125, v130, s[98:99]
	v_cndmask_b32_e64 v132, v131, v126, s[98:99]
	v_cndmask_b32_e64 v133, v127, v131, s[98:99]
	v_cvt_pk_bf16_f32 v128, v128, v129
	v_cvt_pk_bf16_f32 v132, v132, v133
	global_store_dword v120, v128, s[2:3]
	global_store_dword v123, v132, s[2:3]
	v_mul_f32_e32 v124, 0xbfb8aa3b, v84
	v_mul_f32_e32 v125, 0xbfb8aa3b, v85
	v_mul_f32_e32 v126, 0xbfb8aa3b, v86
	v_mul_f32_e32 v127, 0xbfb8aa3b, v87
	v_exp_f32_e32 v124, v124
	v_exp_f32_e32 v125, v125
	v_exp_f32_e32 v126, v126
	v_exp_f32_e32 v127, v127
	v_add_f32_e32 v124, 1.0, v124
	v_add_f32_e32 v125, 1.0, v125
	v_add_f32_e32 v126, 1.0, v126
	v_add_f32_e32 v127, 1.0, v127
	v_rcp_f32_e32 v124, v124
	v_rcp_f32_e32 v125, v125
	v_rcp_f32_e32 v126, v126
	v_rcp_f32_e32 v127, v127
	v_mul_f32_e32 v124, v84, v124
	v_mul_f32_e32 v125, v85, v125
	v_mul_f32_e32 v126, v86, v126
	v_mul_f32_e32 v127, v87, v127
	v_mul_f32_e32 v124, v80, v124
	v_mul_f32_e32 v125, v81, v125
	v_mul_f32_e32 v126, v82, v126
	v_mul_f32_e32 v127, v83, v127
	v_cndmask_b32_e64 v128, v124, v125, s[98:99]
	v_cndmask_b32_e64 v129, v126, v127, s[98:99]
	s_nop 1
	v_mov_b32_dpp v130, v128 quad_perm:[1,0,3,2] row_mask:0xf bank_mask:0xf
	v_mov_b32_dpp v131, v129 quad_perm:[1,0,3,2] row_mask:0xf bank_mask:0xf
	s_nop 0
	v_cndmask_b32_e64 v128, v130, v124, s[98:99]
	v_cndmask_b32_e64 v129, v125, v130, s[98:99]
	v_cndmask_b32_e64 v132, v131, v126, s[98:99]
	v_cndmask_b32_e64 v133, v127, v131, s[98:99]
	v_cvt_pk_bf16_f32 v128, v128, v129
	v_cvt_pk_bf16_f32 v132, v132, v133
	global_store_dword v120, v128, s[2:3] offset:32
	global_store_dword v123, v132, s[2:3] offset:32
	s_add_u32 s2, s2, 0x10000
	s_addc_u32 s3, s3, 0
	v_mul_f32_e32 v124, 0xbfb8aa3b, v76
	v_mul_f32_e32 v125, 0xbfb8aa3b, v77
	v_mul_f32_e32 v126, 0xbfb8aa3b, v78
	v_mul_f32_e32 v127, 0xbfb8aa3b, v79
	v_exp_f32_e32 v124, v124
	v_exp_f32_e32 v125, v125
	v_exp_f32_e32 v126, v126
	v_exp_f32_e32 v127, v127
	v_add_f32_e32 v124, 1.0, v124
	v_add_f32_e32 v125, 1.0, v125
	v_add_f32_e32 v126, 1.0, v126
	v_add_f32_e32 v127, 1.0, v127
	v_rcp_f32_e32 v124, v124
	v_rcp_f32_e32 v125, v125
	v_rcp_f32_e32 v126, v126
	v_rcp_f32_e32 v127, v127
	v_mul_f32_e32 v124, v76, v124
	v_mul_f32_e32 v125, v77, v125
	v_mul_f32_e32 v126, v78, v126
	v_mul_f32_e32 v127, v79, v127
	v_mul_f32_e32 v124, v72, v124
	v_mul_f32_e32 v125, v73, v125
	v_mul_f32_e32 v126, v74, v126
	v_mul_f32_e32 v127, v75, v127
	v_cndmask_b32_e64 v128, v124, v125, s[98:99]
	v_cndmask_b32_e64 v129, v126, v127, s[98:99]
	s_nop 1
	v_mov_b32_dpp v130, v128 quad_perm:[1,0,3,2] row_mask:0xf bank_mask:0xf
	v_mov_b32_dpp v131, v129 quad_perm:[1,0,3,2] row_mask:0xf bank_mask:0xf
	s_nop 0
	v_cndmask_b32_e64 v128, v130, v124, s[98:99]
	v_cndmask_b32_e64 v129, v125, v130, s[98:99]
	v_cndmask_b32_e64 v132, v131, v126, s[98:99]
	v_cndmask_b32_e64 v133, v127, v131, s[98:99]
	v_cvt_pk_bf16_f32 v128, v128, v129
	v_cvt_pk_bf16_f32 v132, v132, v133
	global_store_dword v120, v128, s[2:3]
	global_store_dword v123, v132, s[2:3]
	v_mul_f32_e32 v124, 0xbfb8aa3b, v68
	v_mul_f32_e32 v125, 0xbfb8aa3b, v69
	v_mul_f32_e32 v126, 0xbfb8aa3b, v70
	v_mul_f32_e32 v127, 0xbfb8aa3b, v71
	v_exp_f32_e32 v124, v124
	v_exp_f32_e32 v125, v125
	v_exp_f32_e32 v126, v126
	v_exp_f32_e32 v127, v127
	v_add_f32_e32 v124, 1.0, v124
	v_add_f32_e32 v125, 1.0, v125
	v_add_f32_e32 v126, 1.0, v126
	v_add_f32_e32 v127, 1.0, v127
	v_rcp_f32_e32 v124, v124
	v_rcp_f32_e32 v125, v125
	v_rcp_f32_e32 v126, v126
	v_rcp_f32_e32 v127, v127
	v_mul_f32_e32 v124, v68, v124
	v_mul_f32_e32 v125, v69, v125
	v_mul_f32_e32 v126, v70, v126
	v_mul_f32_e32 v127, v71, v127
	v_mul_f32_e32 v124, v64, v124
	v_mul_f32_e32 v125, v65, v125
	v_mul_f32_e32 v126, v66, v126
	v_mul_f32_e32 v127, v67, v127
	v_cndmask_b32_e64 v128, v124, v125, s[98:99]
	v_cndmask_b32_e64 v129, v126, v127, s[98:99]
	s_nop 1
	v_mov_b32_dpp v130, v128 quad_perm:[1,0,3,2] row_mask:0xf bank_mask:0xf
	v_mov_b32_dpp v131, v129 quad_perm:[1,0,3,2] row_mask:0xf bank_mask:0xf
	s_nop 0
	v_cndmask_b32_e64 v128, v130, v124, s[98:99]
	v_cndmask_b32_e64 v129, v125, v130, s[98:99]
	v_cndmask_b32_e64 v132, v131, v126, s[98:99]
	v_cndmask_b32_e64 v133, v127, v131, s[98:99]
	v_cvt_pk_bf16_f32 v128, v128, v129
	v_cvt_pk_bf16_f32 v132, v132, v133
	global_store_dword v120, v128, s[2:3] offset:32
	global_store_dword v123, v132, s[2:3] offset:32
	s_add_u32 s2, s2, 0x10000
	s_addc_u32 s3, s3, 0
	v_mul_f32_e32 v124, 0xbfb8aa3b, v60
	v_mul_f32_e32 v125, 0xbfb8aa3b, v61
	v_mul_f32_e32 v126, 0xbfb8aa3b, v62
	v_mul_f32_e32 v127, 0xbfb8aa3b, v63
	v_exp_f32_e32 v124, v124
	v_exp_f32_e32 v125, v125
	v_exp_f32_e32 v126, v126
	v_exp_f32_e32 v127, v127
	v_add_f32_e32 v124, 1.0, v124
	v_add_f32_e32 v125, 1.0, v125
	v_add_f32_e32 v126, 1.0, v126
	v_add_f32_e32 v127, 1.0, v127
	v_rcp_f32_e32 v124, v124
	v_rcp_f32_e32 v125, v125
	v_rcp_f32_e32 v126, v126
	v_rcp_f32_e32 v127, v127
	v_mul_f32_e32 v124, v60, v124
	v_mul_f32_e32 v125, v61, v125
	v_mul_f32_e32 v126, v62, v126
	v_mul_f32_e32 v127, v63, v127
	v_mul_f32_e32 v124, v56, v124
	v_mul_f32_e32 v125, v57, v125
	v_mul_f32_e32 v126, v58, v126
	v_mul_f32_e32 v127, v59, v127
	v_cndmask_b32_e64 v128, v124, v125, s[98:99]
	v_cndmask_b32_e64 v129, v126, v127, s[98:99]
	s_nop 1
	v_mov_b32_dpp v130, v128 quad_perm:[1,0,3,2] row_mask:0xf bank_mask:0xf
	v_mov_b32_dpp v131, v129 quad_perm:[1,0,3,2] row_mask:0xf bank_mask:0xf
	s_nop 0
	v_cndmask_b32_e64 v128, v130, v124, s[98:99]
	v_cndmask_b32_e64 v129, v125, v130, s[98:99]
	v_cndmask_b32_e64 v132, v131, v126, s[98:99]
	v_cndmask_b32_e64 v133, v127, v131, s[98:99]
	v_cvt_pk_bf16_f32 v128, v128, v129
	v_cvt_pk_bf16_f32 v132, v132, v133
	global_store_dword v120, v128, s[2:3]
	global_store_dword v123, v132, s[2:3]
	v_mul_f32_e32 v124, 0xbfb8aa3b, v52
	v_mul_f32_e32 v125, 0xbfb8aa3b, v53
	v_mul_f32_e32 v126, 0xbfb8aa3b, v54
	v_mul_f32_e32 v127, 0xbfb8aa3b, v55
	v_exp_f32_e32 v124, v124
	v_exp_f32_e32 v125, v125
	v_exp_f32_e32 v126, v126
	v_exp_f32_e32 v127, v127
	v_add_f32_e32 v124, 1.0, v124
	v_add_f32_e32 v125, 1.0, v125
	v_add_f32_e32 v126, 1.0, v126
	v_add_f32_e32 v127, 1.0, v127
	v_rcp_f32_e32 v124, v124
	v_rcp_f32_e32 v125, v125
	v_rcp_f32_e32 v126, v126
	v_rcp_f32_e32 v127, v127
	v_mul_f32_e32 v124, v52, v124
	v_mul_f32_e32 v125, v53, v125
	v_mul_f32_e32 v126, v54, v126
	v_mul_f32_e32 v127, v55, v127
	v_mul_f32_e32 v124, v48, v124
	v_mul_f32_e32 v125, v49, v125
	v_mul_f32_e32 v126, v50, v126
	v_mul_f32_e32 v127, v51, v127
	v_cndmask_b32_e64 v128, v124, v125, s[98:99]
	v_cndmask_b32_e64 v129, v126, v127, s[98:99]
	s_nop 1
	v_mov_b32_dpp v130, v128 quad_perm:[1,0,3,2] row_mask:0xf bank_mask:0xf
	v_mov_b32_dpp v131, v129 quad_perm:[1,0,3,2] row_mask:0xf bank_mask:0xf
	s_nop 0
	v_cndmask_b32_e64 v128, v130, v124, s[98:99]
	v_cndmask_b32_e64 v129, v125, v130, s[98:99]
	v_cndmask_b32_e64 v132, v131, v126, s[98:99]
	v_cndmask_b32_e64 v133, v127, v131, s[98:99]
	v_cvt_pk_bf16_f32 v128, v128, v129
	v_cvt_pk_bf16_f32 v132, v132, v133
	global_store_dword v120, v128, s[2:3] offset:32
	global_store_dword v123, v132, s[2:3] offset:32
	s_add_u32 s2, s2, 0x10000
	s_addc_u32 s3, s3, 0
	v_mul_f32_e32 v124, 0xbfb8aa3b, v44
	v_mul_f32_e32 v125, 0xbfb8aa3b, v45
	v_mul_f32_e32 v126, 0xbfb8aa3b, v46
	v_mul_f32_e32 v127, 0xbfb8aa3b, v47
	v_exp_f32_e32 v124, v124
	v_exp_f32_e32 v125, v125
	v_exp_f32_e32 v126, v126
	v_exp_f32_e32 v127, v127
	v_add_f32_e32 v124, 1.0, v124
	v_add_f32_e32 v125, 1.0, v125
	v_add_f32_e32 v126, 1.0, v126
	v_add_f32_e32 v127, 1.0, v127
	v_rcp_f32_e32 v124, v124
	v_rcp_f32_e32 v125, v125
	v_rcp_f32_e32 v126, v126
	v_rcp_f32_e32 v127, v127
	v_mul_f32_e32 v124, v44, v124
	v_mul_f32_e32 v125, v45, v125
	v_mul_f32_e32 v126, v46, v126
	v_mul_f32_e32 v127, v47, v127
	v_mul_f32_e32 v124, v40, v124
	v_mul_f32_e32 v125, v41, v125
	v_mul_f32_e32 v126, v42, v126
	v_mul_f32_e32 v127, v43, v127
	v_cndmask_b32_e64 v128, v124, v125, s[98:99]
	v_cndmask_b32_e64 v129, v126, v127, s[98:99]
	s_nop 1
	v_mov_b32_dpp v130, v128 quad_perm:[1,0,3,2] row_mask:0xf bank_mask:0xf
	v_mov_b32_dpp v131, v129 quad_perm:[1,0,3,2] row_mask:0xf bank_mask:0xf
	s_nop 0
	v_cndmask_b32_e64 v128, v130, v124, s[98:99]
	v_cndmask_b32_e64 v129, v125, v130, s[98:99]
	v_cndmask_b32_e64 v132, v131, v126, s[98:99]
	v_cndmask_b32_e64 v133, v127, v131, s[98:99]
	v_cvt_pk_bf16_f32 v128, v128, v129
	v_cvt_pk_bf16_f32 v132, v132, v133
	global_store_dword v120, v128, s[2:3]
	global_store_dword v123, v132, s[2:3]
	v_mul_f32_e32 v124, 0xbfb8aa3b, v36
	v_mul_f32_e32 v125, 0xbfb8aa3b, v37
	v_mul_f32_e32 v126, 0xbfb8aa3b, v38
	v_mul_f32_e32 v127, 0xbfb8aa3b, v39
	v_exp_f32_e32 v124, v124
	v_exp_f32_e32 v125, v125
	v_exp_f32_e32 v126, v126
	v_exp_f32_e32 v127, v127
	v_add_f32_e32 v124, 1.0, v124
	v_add_f32_e32 v125, 1.0, v125
	v_add_f32_e32 v126, 1.0, v126
	v_add_f32_e32 v127, 1.0, v127
	v_rcp_f32_e32 v124, v124
	v_rcp_f32_e32 v125, v125
	v_rcp_f32_e32 v126, v126
	v_rcp_f32_e32 v127, v127
	v_mul_f32_e32 v124, v36, v124
	v_mul_f32_e32 v125, v37, v125
	v_mul_f32_e32 v126, v38, v126
	v_mul_f32_e32 v127, v39, v127
	v_mul_f32_e32 v124, v32, v124
	v_mul_f32_e32 v125, v33, v125
	v_mul_f32_e32 v126, v34, v126
	v_mul_f32_e32 v127, v35, v127
	v_cndmask_b32_e64 v128, v124, v125, s[98:99]
	v_cndmask_b32_e64 v129, v126, v127, s[98:99]
	s_nop 1
	v_mov_b32_dpp v130, v128 quad_perm:[1,0,3,2] row_mask:0xf bank_mask:0xf
	v_mov_b32_dpp v131, v129 quad_perm:[1,0,3,2] row_mask:0xf bank_mask:0xf
	s_nop 0
	v_cndmask_b32_e64 v128, v130, v124, s[98:99]
	v_cndmask_b32_e64 v129, v125, v130, s[98:99]
	v_cndmask_b32_e64 v132, v131, v126, s[98:99]
	v_cndmask_b32_e64 v133, v127, v131, s[98:99]
	v_cvt_pk_bf16_f32 v128, v128, v129
	v_cvt_pk_bf16_f32 v132, v132, v133
	global_store_dword v120, v128, s[2:3] offset:32
	global_store_dword v123, v132, s[2:3] offset:32
	s_add_u32 s2, s2, 0x10000
	s_addc_u32 s3, s3, 0
	v_mul_f32_e32 v124, 0xbfb8aa3b, v24
	v_mul_f32_e32 v125, 0xbfb8aa3b, v25
	v_mul_f32_e32 v126, 0xbfb8aa3b, v26
	v_mul_f32_e32 v127, 0xbfb8aa3b, v27
	v_exp_f32_e32 v124, v124
	v_exp_f32_e32 v125, v125
	v_exp_f32_e32 v126, v126
	v_exp_f32_e32 v127, v127
	v_add_f32_e32 v124, 1.0, v124
	v_add_f32_e32 v125, 1.0, v125
	v_add_f32_e32 v126, 1.0, v126
	v_add_f32_e32 v127, 1.0, v127
	v_rcp_f32_e32 v124, v124
	v_rcp_f32_e32 v125, v125
	v_rcp_f32_e32 v126, v126
	v_rcp_f32_e32 v127, v127
	v_mul_f32_e32 v124, v24, v124
	v_mul_f32_e32 v125, v25, v125
	v_mul_f32_e32 v126, v26, v126
	v_mul_f32_e32 v127, v27, v127
	v_mul_f32_e32 v124, v28, v124
	v_mul_f32_e32 v125, v29, v125
	v_mul_f32_e32 v126, v30, v126
	v_mul_f32_e32 v127, v31, v127
	v_cndmask_b32_e64 v128, v124, v125, s[98:99]
	v_cndmask_b32_e64 v129, v126, v127, s[98:99]
	s_nop 1
	v_mov_b32_dpp v130, v128 quad_perm:[1,0,3,2] row_mask:0xf bank_mask:0xf
	v_mov_b32_dpp v131, v129 quad_perm:[1,0,3,2] row_mask:0xf bank_mask:0xf
	s_nop 0
	v_cndmask_b32_e64 v128, v130, v124, s[98:99]
	v_cndmask_b32_e64 v129, v125, v130, s[98:99]
	v_cndmask_b32_e64 v132, v131, v126, s[98:99]
	v_cndmask_b32_e64 v133, v127, v131, s[98:99]
	v_cvt_pk_bf16_f32 v128, v128, v129
	v_cvt_pk_bf16_f32 v132, v132, v133
	global_store_dword v120, v128, s[2:3]
	global_store_dword v123, v132, s[2:3]
	v_mul_f32_e32 v124, 0xbfb8aa3b, v16
	v_mul_f32_e32 v125, 0xbfb8aa3b, v17
	v_mul_f32_e32 v126, 0xbfb8aa3b, v18
	v_mul_f32_e32 v127, 0xbfb8aa3b, v19
	v_exp_f32_e32 v124, v124
	v_exp_f32_e32 v125, v125
	v_exp_f32_e32 v126, v126
	v_exp_f32_e32 v127, v127
	v_add_f32_e32 v124, 1.0, v124
	v_add_f32_e32 v125, 1.0, v125
	v_add_f32_e32 v126, 1.0, v126
	v_add_f32_e32 v127, 1.0, v127
	v_rcp_f32_e32 v124, v124
	v_rcp_f32_e32 v125, v125
	v_rcp_f32_e32 v126, v126
	v_rcp_f32_e32 v127, v127
	v_mul_f32_e32 v124, v16, v124
	v_mul_f32_e32 v125, v17, v125
	v_mul_f32_e32 v126, v18, v126
	v_mul_f32_e32 v127, v19, v127
	v_mul_f32_e32 v124, v20, v124
	v_mul_f32_e32 v125, v21, v125
	v_mul_f32_e32 v126, v22, v126
	v_mul_f32_e32 v127, v23, v127
	v_cndmask_b32_e64 v128, v124, v125, s[98:99]
	v_cndmask_b32_e64 v129, v126, v127, s[98:99]
	s_nop 1
	v_mov_b32_dpp v130, v128 quad_perm:[1,0,3,2] row_mask:0xf bank_mask:0xf
	v_mov_b32_dpp v131, v129 quad_perm:[1,0,3,2] row_mask:0xf bank_mask:0xf
	s_nop 0
	v_cndmask_b32_e64 v128, v130, v124, s[98:99]
	v_cndmask_b32_e64 v129, v125, v130, s[98:99]
	v_cndmask_b32_e64 v132, v131, v126, s[98:99]
	v_cndmask_b32_e64 v133, v127, v131, s[98:99]
	v_cvt_pk_bf16_f32 v128, v128, v129
	v_cvt_pk_bf16_f32 v132, v132, v133
	global_store_dword v120, v128, s[2:3] offset:32
	global_store_dword v123, v132, s[2:3] offset:32
	s_add_u32 s2, s2, 0x10000
	s_addc_u32 s3, s3, 0
	v_mul_f32_e32 v124, 0xbfb8aa3b, v8
	v_mul_f32_e32 v125, 0xbfb8aa3b, v9
	v_mul_f32_e32 v126, 0xbfb8aa3b, v10
	v_mul_f32_e32 v127, 0xbfb8aa3b, v11
	v_exp_f32_e32 v124, v124
	v_exp_f32_e32 v125, v125
	v_exp_f32_e32 v126, v126
	v_exp_f32_e32 v127, v127
	v_add_f32_e32 v124, 1.0, v124
	v_add_f32_e32 v125, 1.0, v125
	v_add_f32_e32 v126, 1.0, v126
	v_add_f32_e32 v127, 1.0, v127
	v_rcp_f32_e32 v124, v124
	v_rcp_f32_e32 v125, v125
	v_rcp_f32_e32 v126, v126
	v_rcp_f32_e32 v127, v127
	v_mul_f32_e32 v124, v8, v124
	v_mul_f32_e32 v125, v9, v125
	v_mul_f32_e32 v126, v10, v126
	v_mul_f32_e32 v127, v11, v127
	v_mul_f32_e32 v124, v12, v124
	v_mul_f32_e32 v125, v13, v125
	v_mul_f32_e32 v126, v14, v126
	v_mul_f32_e32 v127, v15, v127
	v_cndmask_b32_e64 v128, v124, v125, s[98:99]
	v_cndmask_b32_e64 v129, v126, v127, s[98:99]
	s_nop 1
	v_mov_b32_dpp v130, v128 quad_perm:[1,0,3,2] row_mask:0xf bank_mask:0xf
	v_mov_b32_dpp v131, v129 quad_perm:[1,0,3,2] row_mask:0xf bank_mask:0xf
	s_nop 0
	v_cndmask_b32_e64 v128, v130, v124, s[98:99]
	v_cndmask_b32_e64 v129, v125, v130, s[98:99]
	v_cndmask_b32_e64 v132, v131, v126, s[98:99]
	v_cndmask_b32_e64 v133, v127, v131, s[98:99]
	v_cvt_pk_bf16_f32 v128, v128, v129
	v_cvt_pk_bf16_f32 v132, v132, v133
	global_store_dword v120, v128, s[2:3]
	global_store_dword v123, v132, s[2:3]
	v_mul_f32_e32 v124, 0xbfb8aa3b, v0
	v_mul_f32_e32 v125, 0xbfb8aa3b, v1
	v_mul_f32_e32 v126, 0xbfb8aa3b, v2
	v_mul_f32_e32 v127, 0xbfb8aa3b, v3
	v_exp_f32_e32 v124, v124
	v_exp_f32_e32 v125, v125
	v_exp_f32_e32 v126, v126
	v_exp_f32_e32 v127, v127
	v_add_f32_e32 v124, 1.0, v124
	v_add_f32_e32 v125, 1.0, v125
	v_add_f32_e32 v126, 1.0, v126
	v_add_f32_e32 v127, 1.0, v127
	v_rcp_f32_e32 v124, v124
	v_rcp_f32_e32 v125, v125
	v_rcp_f32_e32 v126, v126
	v_rcp_f32_e32 v127, v127
	v_mul_f32_e32 v124, v0, v124
	v_mul_f32_e32 v125, v1, v125
	v_mul_f32_e32 v126, v2, v126
	v_mul_f32_e32 v127, v3, v127
	v_mul_f32_e32 v124, v4, v124
	v_mul_f32_e32 v125, v5, v125
	v_mul_f32_e32 v126, v6, v126
	v_mul_f32_e32 v127, v7, v127
	v_cndmask_b32_e64 v128, v124, v125, s[98:99]
	v_cndmask_b32_e64 v129, v126, v127, s[98:99]
	s_nop 1
	v_mov_b32_dpp v130, v128 quad_perm:[1,0,3,2] row_mask:0xf bank_mask:0xf
	v_mov_b32_dpp v131, v129 quad_perm:[1,0,3,2] row_mask:0xf bank_mask:0xf
	s_nop 0
	v_cndmask_b32_e64 v128, v130, v124, s[98:99]
	v_cndmask_b32_e64 v129, v125, v130, s[98:99]
	v_cndmask_b32_e64 v132, v131, v126, s[98:99]
	v_cndmask_b32_e64 v133, v127, v131, s[98:99]
	v_cvt_pk_bf16_f32 v128, v128, v129
	v_cvt_pk_bf16_f32 v132, v132, v133
	global_store_dword v120, v128, s[2:3] offset:32
	global_store_dword v123, v132, s[2:3] offset:32
	s_add_i32 s17, s17, s92
	s_cmpk_lt_i32 s17, 0x800
	s_cbranch_scc0 .LBB0_1188
